# 64 x v_mov_b64 accumulator clear also in the FFN-out, mixer-in and mixer-out GEMM instances
# speedup vs baseline: 1.0060x; 1.0055x over previous
.LBB0_458:
	s_add_u32 s17, s20, 0x100
	v_mov_b64_e32 v[0:1], 0
	v_mov_b64_e32 v[2:3], 0
	v_mov_b64_e32 v[4:5], 0
	v_mov_b64_e32 v[6:7], 0
	v_mov_b64_e32 v[8:9], 0
	v_mov_b64_e32 v[10:11], 0
	v_mov_b64_e32 v[12:13], 0
	v_mov_b64_e32 v[14:15], 0
	v_mov_b64_e32 v[16:17], 0
	v_mov_b64_e32 v[18:19], 0
	v_mov_b64_e32 v[20:21], 0
	v_mov_b64_e32 v[22:23], 0
	v_mov_b64_e32 v[24:25], 0
	v_mov_b64_e32 v[26:27], 0
	v_mov_b64_e32 v[28:29], 0
	v_mov_b64_e32 v[30:31], 0
	v_mov_b64_e32 v[32:33], 0
	v_mov_b64_e32 v[34:35], 0
	v_mov_b64_e32 v[36:37], 0
	v_mov_b64_e32 v[38:39], 0
	v_mov_b64_e32 v[40:41], 0
	v_mov_b64_e32 v[42:43], 0
	v_mov_b64_e32 v[44:45], 0
	v_mov_b64_e32 v[46:47], 0
	v_mov_b64_e32 v[48:49], 0
	v_mov_b64_e32 v[50:51], 0
	v_mov_b64_e32 v[52:53], 0
	v_mov_b64_e32 v[54:55], 0
	v_mov_b64_e32 v[56:57], 0
	v_mov_b64_e32 v[58:59], 0
	v_mov_b64_e32 v[60:61], 0
	v_mov_b64_e32 v[62:63], 0
	v_mov_b64_e32 v[64:65], 0
	v_mov_b64_e32 v[66:67], 0
	v_mov_b64_e32 v[68:69], 0
	v_mov_b64_e32 v[70:71], 0
	v_mov_b64_e32 v[72:73], 0
	v_mov_b64_e32 v[74:75], 0
	v_mov_b64_e32 v[76:77], 0
	v_mov_b64_e32 v[78:79], 0
	v_mov_b64_e32 v[80:81], 0
	v_mov_b64_e32 v[82:83], 0
	v_mov_b64_e32 v[84:85], 0
	v_mov_b64_e32 v[86:87], 0
	v_mov_b64_e32 v[88:89], 0
	v_mov_b64_e32 v[90:91], 0
	v_mov_b64_e32 v[92:93], 0
	v_mov_b64_e32 v[94:95], 0
	v_mov_b64_e32 v[96:97], 0
	v_mov_b64_e32 v[98:99], 0
	v_mov_b64_e32 v[100:101], 0
	v_mov_b64_e32 v[102:103], 0
	v_mov_b64_e32 v[104:105], 0
	v_mov_b64_e32 v[106:107], 0
	v_mov_b64_e32 v[108:109], 0
	v_mov_b64_e32 v[110:111], 0
	v_mov_b64_e32 v[112:113], 0
	v_mov_b64_e32 v[114:115], 0
	v_mov_b64_e32 v[116:117], 0
	v_mov_b64_e32 v[118:119], 0
	v_mov_b64_e32 v[120:121], 0
	v_mov_b64_e32 v[122:123], 0
	v_mov_b64_e32 v[124:125], 0
	v_mov_b64_e32 v[126:127], 0
	s_addc_u32 s56, s21, 0
	s_mov_b32 s57, -2

.LBB0_593:
	s_ashr_i32 s95, s94, 31
	s_lshl_b64 s[26:27], s[94:95], 19
	s_add_u32 s7, s51, s26
	s_addc_u32 s9, s71, s27
	s_ashr_i32 s93, s92, 31
	s_lshl_b64 s[26:27], s[92:93], 11
	s_add_u32 s96, s7, s26
	s_addc_u32 s97, s9, s27
	s_and_b64 s[30:31], s[10:11], exec
	s_cselect_b32 s7, s97, s5
	s_cselect_b32 s9, s96, s4
	s_ashr_i32 s91, s90, 31
	s_lshl_b64 s[30:31], s[90:91], 19
	s_add_u32 s30, s78, s30
	s_addc_u32 s31, s79, s31
	s_add_u32 s56, s30, s26
	s_addc_u32 s57, s31, s27
	s_and_b64 s[26:27], s[10:11], exec
	s_cselect_b32 s26, s57, s43
	s_cselect_b32 s27, s56, s42
	s_add_u32 s4, s4, 0x40080
	s_addc_u32 s5, s5, 0
	s_add_u32 s30, s42, 0x100
	v_mov_b64_e32 v[0:1], 0
	v_mov_b64_e32 v[2:3], 0
	v_mov_b64_e32 v[4:5], 0
	v_mov_b64_e32 v[6:7], 0
	v_mov_b64_e32 v[8:9], 0
	v_mov_b64_e32 v[10:11], 0
	v_mov_b64_e32 v[12:13], 0
	v_mov_b64_e32 v[14:15], 0
	v_mov_b64_e32 v[16:17], 0
	v_mov_b64_e32 v[18:19], 0
	v_mov_b64_e32 v[20:21], 0
	v_mov_b64_e32 v[22:23], 0
	v_mov_b64_e32 v[24:25], 0
	v_mov_b64_e32 v[26:27], 0
	v_mov_b64_e32 v[28:29], 0
	v_mov_b64_e32 v[30:31], 0
	v_mov_b64_e32 v[32:33], 0
	v_mov_b64_e32 v[34:35], 0
	v_mov_b64_e32 v[36:37], 0
	v_mov_b64_e32 v[38:39], 0
	v_mov_b64_e32 v[40:41], 0
	v_mov_b64_e32 v[42:43], 0
	v_mov_b64_e32 v[44:45], 0
	v_mov_b64_e32 v[46:47], 0
	v_mov_b64_e32 v[48:49], 0
	v_mov_b64_e32 v[50:51], 0
	v_mov_b64_e32 v[52:53], 0
	v_mov_b64_e32 v[54:55], 0
	v_mov_b64_e32 v[56:57], 0
	v_mov_b64_e32 v[58:59], 0
	v_mov_b64_e32 v[60:61], 0
	v_mov_b64_e32 v[62:63], 0
	v_mov_b64_e32 v[64:65], 0
	v_mov_b64_e32 v[66:67], 0
	v_mov_b64_e32 v[68:69], 0
	v_mov_b64_e32 v[70:71], 0
	v_mov_b64_e32 v[72:73], 0
	v_mov_b64_e32 v[74:75], 0
	v_mov_b64_e32 v[76:77], 0
	v_mov_b64_e32 v[78:79], 0
	v_mov_b64_e32 v[80:81], 0
	v_mov_b64_e32 v[82:83], 0
	v_mov_b64_e32 v[84:85], 0
	v_mov_b64_e32 v[86:87], 0
	v_mov_b64_e32 v[88:89], 0
	v_mov_b64_e32 v[90:91], 0
	v_mov_b64_e32 v[92:93], 0
	v_mov_b64_e32 v[94:95], 0
	v_mov_b64_e32 v[96:97], 0
	v_mov_b64_e32 v[98:99], 0
	v_mov_b64_e32 v[100:101], 0
	v_mov_b64_e32 v[102:103], 0
	v_mov_b64_e32 v[104:105], 0
	v_mov_b64_e32 v[106:107], 0
	v_mov_b64_e32 v[108:109], 0
	v_mov_b64_e32 v[110:111], 0
	v_mov_b64_e32 v[112:113], 0
	v_mov_b64_e32 v[114:115], 0
	v_mov_b64_e32 v[116:117], 0
	v_mov_b64_e32 v[118:119], 0
	v_mov_b64_e32 v[120:121], 0
	v_mov_b64_e32 v[122:123], 0
	v_mov_b64_e32 v[124:125], 0
	v_mov_b64_e32 v[126:127], 0
	s_addc_u32 s31, s43, 0
	s_mov_b32 s36, -2

.LBB0_1161:
	s_ashr_i32 s17, s16, 31
	s_lshl_b64 s[18:19], s[16:17], 19
	s_add_u32 s13, s27, s18
	s_addc_u32 s17, s30, s19
	s_ashr_i32 s15, s14, 31
	s_lshl_b64 s[20:21], s[14:15], 10
	s_add_u32 s18, s13, s20
	s_addc_u32 s19, s17, s21
	s_and_b64 s[56:57], s[4:5], exec
	s_cselect_b32 s15, s19, s55
	s_cselect_b32 s17, s18, s54
	s_ashr_i32 s13, s12, 31
	s_lshl_b64 s[56:57], s[12:13], 19
	s_add_u32 s13, s31, s56
	s_addc_u32 s25, s33, s57
	s_add_u32 s20, s13, s20
	s_addc_u32 s21, s25, s21
	s_and_b64 s[56:57], s[4:5], exec
	s_cselect_b32 s13, s21, s43
	s_cselect_b32 s25, s20, s42
	s_add_u32 s56, s54, 0x40080
	s_addc_u32 s57, s55, 0
	s_add_u32 s53, s42, 0x100
	v_mov_b64_e32 v[0:1], 0
	v_mov_b64_e32 v[2:3], 0
	v_mov_b64_e32 v[4:5], 0
	v_mov_b64_e32 v[6:7], 0
	v_mov_b64_e32 v[8:9], 0
	v_mov_b64_e32 v[10:11], 0
	v_mov_b64_e32 v[12:13], 0
	v_mov_b64_e32 v[14:15], 0
	v_mov_b64_e32 v[16:17], 0
	v_mov_b64_e32 v[18:19], 0
	v_mov_b64_e32 v[20:21], 0
	v_mov_b64_e32 v[22:23], 0
	v_mov_b64_e32 v[24:25], 0
	v_mov_b64_e32 v[26:27], 0
	v_mov_b64_e32 v[28:29], 0
	v_mov_b64_e32 v[30:31], 0
	v_mov_b64_e32 v[32:33], 0
	v_mov_b64_e32 v[34:35], 0
	v_mov_b64_e32 v[36:37], 0
	v_mov_b64_e32 v[38:39], 0
	v_mov_b64_e32 v[40:41], 0
	v_mov_b64_e32 v[42:43], 0
	v_mov_b64_e32 v[44:45], 0
	v_mov_b64_e32 v[46:47], 0
	v_mov_b64_e32 v[48:49], 0
	v_mov_b64_e32 v[50:51], 0
	v_mov_b64_e32 v[52:53], 0
	v_mov_b64_e32 v[54:55], 0
	v_mov_b64_e32 v[56:57], 0
	v_mov_b64_e32 v[58:59], 0
	v_mov_b64_e32 v[60:61], 0
	v_mov_b64_e32 v[62:63], 0
	v_mov_b64_e32 v[64:65], 0
	v_mov_b64_e32 v[66:67], 0
	v_mov_b64_e32 v[68:69], 0
	v_mov_b64_e32 v[70:71], 0
	v_mov_b64_e32 v[72:73], 0
	v_mov_b64_e32 v[74:75], 0
	v_mov_b64_e32 v[76:77], 0
	v_mov_b64_e32 v[78:79], 0
	v_mov_b64_e32 v[80:81], 0
	v_mov_b64_e32 v[82:83], 0
	v_mov_b64_e32 v[84:85], 0
	v_mov_b64_e32 v[86:87], 0
	v_mov_b64_e32 v[88:89], 0
	v_mov_b64_e32 v[90:91], 0
	v_mov_b64_e32 v[92:93], 0
	v_mov_b64_e32 v[94:95], 0
	v_mov_b64_e32 v[96:97], 0
	v_mov_b64_e32 v[98:99], 0
	v_mov_b64_e32 v[100:101], 0
	v_mov_b64_e32 v[102:103], 0
	v_mov_b64_e32 v[104:105], 0
	v_mov_b64_e32 v[106:107], 0
	v_mov_b64_e32 v[108:109], 0
	v_mov_b64_e32 v[110:111], 0
	v_mov_b64_e32 v[112:113], 0
	v_mov_b64_e32 v[114:115], 0
	v_mov_b64_e32 v[116:117], 0
	v_mov_b64_e32 v[118:119], 0
	v_mov_b64_e32 v[120:121], 0
	v_mov_b64_e32 v[122:123], 0
	v_mov_b64_e32 v[124:125], 0
	v_mov_b64_e32 v[126:127], 0
	s_addc_u32 s58, s43, 0
	s_mov_b32 s59, -2
